# v58 + gla_post next-row prefetch + barrier L1-invalidate issued by wave 1 at barrier entry (12 of 15 copies); K-loop heads re-pinned to the same byte phases
# speedup vs baseline: 1.0111x; 1.0033x over previous
; template <class Epi, class Sched, bool HM = false>
; __device__ __forceinline__ void gemm_phase(PG8_LAS unsigned char* lds, const Gemm g, const Sched& S, const Epi& E) {
;     ...
;     f32x4 acc[2][2][4][2]; f32x4 accx[2];
; #pragma unroll
;     for (int a = 0; a < 2; ++a)
; #pragma unroll
;         for (int b = 0; b < 2; ++b)
; #pragma unroll
;             for (int m = 0; m < 4; ++m)
; #pragma unroll
;                 for (int n = 0; n < 2; ++n) acc[a][b][m][n] = (f32x4){0.f, 0.f, 0.f, 0.f};
;     accx[0] = (f32x4){0.f, 0.f, 0.f, 0.f}; accx[1] = accx[0];
.LBB0_531:
	s_add_u32 s38, s4, 0x100
	s_addc_u32 s39, s5, 0
	v_mov_b32_e32 v4, v3
	v_mov_b32_e32 v5, v3
	s_add_u32 s27, s6, 0x100
	v_mov_b32_e32 v2, v3
	v_mov_b32_e32 v22, 0
	v_mov_b64_e32 v[20:21], v[4:5]
	v_mov_b64_e32 v[16:17], v[4:5]
	s_addc_u32 s82, s7, 0
	s_mov_b32 s22, 0
	s_mov_b32 s23, -2
	v_mov_b64_e32 v[18:19], v[2:3]
	v_mov_b64_e32 v[14:15], v[2:3]
	v_mov_b32_e32 v23, v22
	v_mov_b32_e32 v24, v22
	v_mov_b32_e32 v25, v22
	v_mov_b32_e32 v26, v22
	v_mov_b32_e32 v27, v22
	v_mov_b32_e32 v28, v22
	v_mov_b32_e32 v29, v22
	v_mov_b32_e32 v30, v22
	v_mov_b32_e32 v31, v22
	v_mov_b32_e32 v32, v22
	v_mov_b32_e32 v33, v22
	v_mov_b32_e32 v38, v22
	v_mov_b32_e32 v39, v22
	v_mov_b32_e32 v40, v22
	v_mov_b32_e32 v41, v22
	v_mov_b32_e32 v46, v22
	v_mov_b32_e32 v47, v22
	v_mov_b32_e32 v48, v22
	v_mov_b32_e32 v49, v22
	v_mov_b32_e32 v54, v22
	v_mov_b32_e32 v55, v22
	v_mov_b32_e32 v56, v22
	v_mov_b32_e32 v57, v22
	v_mov_b32_e32 v62, v22
	v_mov_b32_e32 v63, v22
	v_mov_b32_e32 v64, v22
	v_mov_b32_e32 v65, v22
	v_mov_b32_e32 v70, v22
	v_mov_b32_e32 v71, v22
	v_mov_b32_e32 v72, v22
	v_mov_b32_e32 v73, v22
	v_mov_b32_e32 v34, v22
	v_mov_b32_e32 v35, v22
	v_mov_b32_e32 v36, v22
	v_mov_b32_e32 v37, v22
	v_mov_b32_e32 v42, v22
	v_mov_b32_e32 v43, v22
	v_mov_b32_e32 v44, v22
	v_mov_b32_e32 v45, v22
	v_mov_b32_e32 v50, v22
	v_mov_b32_e32 v51, v22
	v_mov_b32_e32 v52, v22
	v_mov_b32_e32 v53, v22
	v_mov_b32_e32 v58, v22
	v_mov_b32_e32 v59, v22
	v_mov_b32_e32 v60, v22
	v_mov_b32_e32 v61, v22
	v_mov_b32_e32 v66, v22
	v_mov_b32_e32 v67, v22
	v_mov_b32_e32 v68, v22
	v_mov_b32_e32 v69, v22
	v_mov_b32_e32 v74, v22
	v_mov_b32_e32 v75, v22
	v_mov_b32_e32 v76, v22
	v_mov_b32_e32 v77, v22
	v_mov_b32_e32 v78, v22
	v_mov_b32_e32 v79, v22
	v_mov_b32_e32 v80, v22
	v_mov_b32_e32 v81, v22
	v_mov_b32_e32 v82, v22
	v_mov_b32_e32 v83, v22
	v_mov_b32_e32 v84, v22
	v_mov_b32_e32 v85, v22
	v_mov_b32_e32 v86, v22
	v_mov_b32_e32 v87, v22
	v_mov_b32_e32 v88, v22
	v_mov_b32_e32 v89, v22
	v_mov_b32_e32 v90, v22
	v_mov_b32_e32 v91, v22
	v_mov_b32_e32 v92, v22
	v_mov_b32_e32 v93, v22
	v_mov_b32_e32 v94, v22
	v_mov_b32_e32 v95, v22
	v_mov_b32_e32 v96, v22
	v_mov_b32_e32 v97, v22
	v_mov_b32_e32 v102, v22
	v_mov_b32_e32 v103, v22
	v_mov_b32_e32 v104, v22
	v_mov_b32_e32 v105, v22
	v_mov_b32_e32 v110, v22
	v_mov_b32_e32 v111, v22
	v_mov_b32_e32 v112, v22
	v_mov_b32_e32 v113, v22
	v_mov_b32_e32 v118, v22
	v_mov_b32_e32 v119, v22
	v_mov_b32_e32 v120, v22
	v_mov_b32_e32 v121, v22
	v_mov_b32_e32 v126, v22
	v_mov_b32_e32 v127, v22
	v_mov_b32_e32 v128, v22
	v_mov_b32_e32 v129, v22
	v_mov_b32_e32 v134, v22
	v_mov_b32_e32 v135, v22
	v_mov_b32_e32 v136, v22
	v_mov_b32_e32 v137, v22
	v_mov_b32_e32 v98, v22
	v_mov_b32_e32 v99, v22
	v_mov_b32_e32 v100, v22
	v_mov_b32_e32 v101, v22
	v_mov_b32_e32 v106, v22
	v_mov_b32_e32 v107, v22
	v_mov_b32_e32 v108, v22
	v_mov_b32_e32 v109, v22
	v_mov_b32_e32 v114, v22
	v_mov_b32_e32 v115, v22
	v_mov_b32_e32 v116, v22
	v_mov_b32_e32 v117, v22
	v_mov_b32_e32 v122, v22
	v_mov_b32_e32 v123, v22
	v_mov_b32_e32 v124, v22
	v_mov_b32_e32 v125, v22
	v_mov_b32_e32 v130, v22
	v_mov_b32_e32 v131, v22
	v_mov_b32_e32 v132, v22
	v_mov_b32_e32 v133, v22
	v_mov_b32_e32 v138, v22
	v_mov_b32_e32 v139, v22
	v_mov_b32_e32 v140, v22
	v_mov_b32_e32 v141, v22
	v_mov_b32_e32 v142, v22
	v_mov_b32_e32 v143, v22
	v_mov_b32_e32 v144, v22
	v_mov_b32_e32 v145, v22
	v_mov_b32_e32 v146, v22
	v_mov_b32_e32 v147, v22
	v_mov_b32_e32 v148, v22
	v_mov_b32_e32 v149, v22
	s_nop 0
	s_branch .LBB0_534
